# one static s_setprio 1 for the workgroup that registered second on its CU (two waves per SIMD), set once after the first grid barrier
# speedup vs baseline: 1.0163x; 1.0163x over previous
.LBB0_61:
	s_cmp_eq_u32 s17, 1
	s_cbranch_scc0 .Lbar_chk_done
	s_mov_b64 exec, 1
	v_readlane_b32 s4, v252, 4
	v_readlane_b32 s5, v252, 5
	v_mov_b32_e32 v3, 0x3400
	s_nop 3
	global_load_dwordx4 v[4:7], v3, s[4:5] sc1
	global_load_dwordx4 v[8:11], v3, s[4:5] offset:16 sc1
	s_mov_b32 s10, 0
	s_mov_b32 s11, 1
	s_waitcnt vmcnt(0)
	v_readfirstlane_b32 s6, v4
	s_bcnt1_i32_b32 s7, s6
	s_cmp_eq_u32 s7, 1
	s_cselect_b32 s11, s11, 0
	s_or_b32 s10, s10, s6
	v_readfirstlane_b32 s6, v5
	s_bcnt1_i32_b32 s7, s6
	s_cmp_eq_u32 s7, 1
	s_cselect_b32 s11, s11, 0
	s_or_b32 s10, s10, s6
	v_readfirstlane_b32 s6, v6
	s_bcnt1_i32_b32 s7, s6
	s_cmp_eq_u32 s7, 1
	s_cselect_b32 s11, s11, 0
	s_or_b32 s10, s10, s6
	v_readfirstlane_b32 s6, v7
	s_bcnt1_i32_b32 s7, s6
	s_cmp_eq_u32 s7, 1
	s_cselect_b32 s11, s11, 0
	s_or_b32 s10, s10, s6
	v_readfirstlane_b32 s6, v8
	s_bcnt1_i32_b32 s7, s6
	s_cmp_eq_u32 s7, 1
	s_cselect_b32 s11, s11, 0
	s_or_b32 s10, s10, s6
	v_readfirstlane_b32 s6, v9
	s_bcnt1_i32_b32 s7, s6
	s_cmp_eq_u32 s7, 1
	s_cselect_b32 s11, s11, 0
	s_or_b32 s10, s10, s6
	v_readfirstlane_b32 s6, v10
	s_bcnt1_i32_b32 s7, s6
	s_cmp_eq_u32 s7, 1
	s_cselect_b32 s11, s11, 0
	s_or_b32 s10, s10, s6
	v_readfirstlane_b32 s6, v11
	s_bcnt1_i32_b32 s7, s6
	s_cmp_eq_u32 s7, 1
	s_cselect_b32 s11, s11, 0
	s_or_b32 s10, s10, s6
	s_bcnt1_i32_b32 s7, s10
	s_cmp_eq_u32 s7, 8
	s_cselect_b32 s11, s11, 0
	v_readlane_b32 s6, v252, 2
	v_readlane_b32 s7, v252, 3
	s_load_dword s6, s[6:7], 0x0
	s_waitcnt lgkmcnt(0)
	s_and_b32 s6, s6, 63
	s_cmp_eq_u32 s6, 0
	s_cselect_b32 s11, s11, 0
	s_nop 0
	v_writelane_b32 v255, s11, 40
	s_mov_b64 exec, -1
	v_mov_b32_e32 v3, 0x12ff8
	ds_read_b32 v3, v3
	s_getreg_b32 s6, hwreg(HW_REG_XCC_ID, 0, 4)
	s_and_b32 s6, s6, 7
	s_lshl_b32 s6, s6, 8
	s_addk_i32 s6, 0x3500
	v_lshl_add_u32 v4, v198, 2, s6
	global_load_dword v4, v4, s[4:5] sc1
	s_getreg_b32 s7, hwreg(HW_REG_HW_ID, 8, 8)
	s_mov_b32 s100, 0
	s_mov_b32 s101, 0
	s_waitcnt vmcnt(0) lgkmcnt(0)
	v_readfirstlane_b32 s10, v3
	v_and_b32_e32 v5, 0xfdfdfdfd, v4
	v_cmp_ne_u32_e32 vcc, 0, v5
	s_cmp_lg_u64 vcc, 0
	s_cselect_b32 s11, 0, s11
	s_cmp_lt_u32 s10, 2
	s_cselect_b32 s11, s11, 0
	s_lshr_b32 s6, s7, 2
	s_lshl_b64 s[4:5], 1, s6
	s_sub_u32 s4, s4, 1
	s_subb_u32 s5, s5, 0
	v_readlane_b32 s6, v4, s6
	s_and_b32 s7, s7, 3
	s_lshl_b32 s7, s7, 3
	s_bfm_b32 s7, s7, 0
	s_and_b32 s6, s6, s7
	s_bcnt1_i32_b32 s101, s6
	v_bfe_u32 v5, v4, 1, 1
	v_cmp_ne_u32_e32 vcc, 0, v5
	s_bcnt1_i32_b64 s6, vcc
	s_add_u32 s100, s100, s6
	s_and_b64 vcc, vcc, s[4:5]
	s_bcnt1_i32_b64 s6, vcc
	s_add_u32 s101, s101, s6
	v_bfe_u32 v5, v4, 9, 1
	v_cmp_ne_u32_e32 vcc, 0, v5
	s_bcnt1_i32_b64 s6, vcc
	s_add_u32 s100, s100, s6
	s_and_b64 vcc, vcc, s[4:5]
	s_bcnt1_i32_b64 s6, vcc
	s_add_u32 s101, s101, s6
	v_bfe_u32 v5, v4, 17, 1
	v_cmp_ne_u32_e32 vcc, 0, v5
	s_bcnt1_i32_b64 s6, vcc
	s_add_u32 s100, s100, s6
	s_and_b64 vcc, vcc, s[4:5]
	s_bcnt1_i32_b64 s6, vcc
	s_add_u32 s101, s101, s6
	v_bfe_u32 v5, v4, 25, 1
	v_cmp_ne_u32_e32 vcc, 0, v5
	s_bcnt1_i32_b64 s6, vcc
	s_add_u32 s100, s100, s6
	s_and_b64 vcc, vcc, s[4:5]
	s_bcnt1_i32_b64 s6, vcc
	s_add_u32 s101, s101, s6
	s_cmp_eq_u32 s100, 32
	s_cselect_b32 s11, s11, 0
	s_lshl_b32 s10, s10, 8
	s_or_b32 s10, s10, s101
	s_cmp_eq_u32 s11, 1
	s_cselect_b32 s10, s10, -1
	s_nop 0
	v_writelane_b32 v255, s10, 49
	s_cmp_eq_u32 s10, -1
	s_cbranch_scc1 .Lbar_chk_done
	s_bitcmp1_b32 s10, 8
	s_cbranch_scc0 .Lbar_chk_done
	s_setprio 1
